# GLA state-scan loop software-pipelined 2-deep (next 24 loads in flight during compute)
# baseline (speedup 1.0000x reference)
.LBB0_407:
	v_add_u32_e32 v38, 0xfffff580, v2
	v_ashrrev_i32_e32 v39, 31, v38
	v_lshlrev_b64 v[38:39], 2, v[38:39]
	v_lshl_add_u64 v[46:47], s[80:81], 0, v[38:39]
	v_lshl_add_u64 v[48:49], s[98:99], 0, v[38:39]
	v_add_u32_e32 v38, 0xfffff700, v2
	v_ashrrev_i32_e32 v39, 31, v38
	v_lshlrev_b64 v[38:39], 2, v[38:39]
	v_lshl_add_u64 v[50:51], s[80:81], 0, v[38:39]
	v_lshl_add_u64 v[52:53], s[98:99], 0, v[38:39]
	v_add_u32_e32 v38, 0xfffff880, v2
	v_ashrrev_i32_e32 v39, 31, v38
	v_lshlrev_b64 v[38:39], 2, v[38:39]
	v_lshl_add_u64 v[54:55], s[80:81], 0, v[38:39]
	v_lshl_add_u64 v[56:57], s[98:99], 0, v[38:39]
	v_add_u32_e32 v38, 0xfffffa00, v2
	v_ashrrev_i32_e32 v39, 31, v38
	v_lshlrev_b64 v[38:39], 2, v[38:39]
	v_lshl_add_u64 v[60:61], s[80:81], 0, v[38:39]
	v_lshl_add_u64 v[68:69], s[98:99], 0, v[38:39]
	v_add_u32_e32 v38, 0xfffffb80, v2
	v_ashrrev_i32_e32 v39, 31, v38
	v_lshlrev_b64 v[38:39], 2, v[38:39]
	v_lshl_add_u64 v[78:79], s[80:81], 0, v[38:39]
	v_lshl_add_u64 v[74:75], s[98:99], 0, v[38:39]
	v_add_u32_e32 v38, 0xfffffd00, v2
	v_ashrrev_i32_e32 v39, 31, v38
	v_lshlrev_b64 v[38:39], 2, v[38:39]
	v_lshl_add_u64 v[82:83], s[80:81], 0, v[38:39]
	v_lshl_add_u64 v[84:85], s[98:99], 0, v[38:39]
	v_add_u32_e32 v38, 0xfffffe80, v2
	v_ashrrev_i32_e32 v39, 31, v38
	v_lshlrev_b64 v[38:39], 2, v[38:39]
	v_ashrrev_i32_e32 v3, 31, v2
	v_lshl_add_u64 v[40:41], s[30:31], 0, v[34:35]
	v_lshl_add_u64 v[44:45], s[30:31], 0, v[30:31]
	v_lshl_add_u64 v[42:43], s[30:31], 0, v[26:27]
	v_lshl_add_u64 v[58:59], s[30:31], 0, v[22:23]
	v_lshl_add_u64 v[76:77], s[30:31], 0, v[18:19]
	v_lshl_add_u64 v[80:81], s[30:31], 0, v[14:15]
	v_lshl_add_u64 v[88:89], s[80:81], 0, v[38:39]
	v_lshl_add_u64 v[90:91], s[98:99], 0, v[38:39]
	v_lshlrev_b64 v[38:39], 2, v[2:3]
	v_lshl_add_u64 v[86:87], s[30:31], 0, v[10:11]
	v_lshl_add_u64 v[92:93], s[30:31], 0, v[6:7]
	v_lshl_add_u64 v[94:95], s[80:81], 0, v[38:39]
	v_lshl_add_u64 v[96:97], s[98:99], 0, v[38:39]
	global_load_dwordx2 v[38:39], v[58:59], off
	s_nop 0
	global_load_dwordx2 v[42:43], v[42:43], off
	s_nop 0
	global_load_dwordx2 v[62:63], v[44:45], off
	global_load_dwordx2 v[66:67], v[40:41], off
	s_nop 0
	global_load_dwordx2 v[40:41], v[60:61], off
	global_load_dwordx2 v[44:45], v[54:55], off
	global_load_dwordx2 v[64:65], v[50:51], off
	global_load_dwordx2 v[70:71], v[46:47], off
	s_nop 0
	global_load_dwordx2 v[46:47], v[68:69], off
	s_nop 0
	global_load_dwordx2 v[68:69], v[56:57], off
	global_load_dwordx2 v[72:73], v[52:53], off
	global_load_dwordx2 v[98:99], v[48:49], off
	s_nop 0
	global_load_dwordx2 v[48:49], v[92:93], off
	global_load_dwordx2 v[50:51], v[86:87], off
	global_load_dwordx2 v[54:55], v[80:81], off
	global_load_dwordx2 v[58:59], v[76:77], off
	global_load_dwordx2 v[52:53], v[88:89], off
	global_load_dwordx2 v[56:57], v[82:83], off
	global_load_dwordx2 v[60:61], v[78:79], off
	s_nop 0
	global_load_dwordx2 v[76:77], v[94:95], off
	global_load_dwordx2 v[78:79], v[90:91], off
	global_load_dwordx2 v[80:81], v[84:85], off
	s_nop 0
	global_load_dwordx2 v[74:75], v[74:75], off
	s_nop 0
	global_load_dwordx2 v[82:83], v[96:97], off
	v_add_u32_e32 v2, 0xc00, v2
	v_lshl_add_u64 v[6:7], v[6:7], 0, s[92:93]
	v_lshl_add_u64 v[10:11], v[10:11], 0, s[92:93]
	v_lshl_add_u64 v[14:15], v[14:15], 0, s[92:93]
	v_lshl_add_u64 v[18:19], v[18:19], 0, s[92:93]
	v_lshl_add_u64 v[22:23], v[22:23], 0, s[92:93]
	v_lshl_add_u64 v[26:27], v[26:27], 0, s[92:93]
	v_lshl_add_u64 v[30:31], v[30:31], 0, s[92:93]
	v_lshl_add_u64 v[34:35], v[34:35], 0, s[92:93]
	s_mov_b32 s10, 0
.Lscan_loop:
	v_add_u32_e32 v100, 0xfffff580, v2
	v_ashrrev_i32_e32 v101, 31, v100
	v_lshlrev_b64 v[100:101], 2, v[100:101]
	v_lshl_add_u64 v[108:109], s[80:81], 0, v[100:101]
	v_lshl_add_u64 v[110:111], s[98:99], 0, v[100:101]
	v_add_u32_e32 v100, 0xfffff700, v2
	v_ashrrev_i32_e32 v101, 31, v100
	v_lshlrev_b64 v[100:101], 2, v[100:101]
	v_lshl_add_u64 v[112:113], s[80:81], 0, v[100:101]
	v_lshl_add_u64 v[114:115], s[98:99], 0, v[100:101]
	v_add_u32_e32 v100, 0xfffff880, v2
	v_ashrrev_i32_e32 v101, 31, v100
	v_lshlrev_b64 v[100:101], 2, v[100:101]
	v_lshl_add_u64 v[116:117], s[80:81], 0, v[100:101]
	v_lshl_add_u64 v[118:119], s[98:99], 0, v[100:101]
	v_add_u32_e32 v100, 0xfffffa00, v2
	v_ashrrev_i32_e32 v101, 31, v100
	v_lshlrev_b64 v[100:101], 2, v[100:101]
	v_lshl_add_u64 v[122:123], s[80:81], 0, v[100:101]
	v_lshl_add_u64 v[130:131], s[98:99], 0, v[100:101]
	v_add_u32_e32 v100, 0xfffffb80, v2
	v_ashrrev_i32_e32 v101, 31, v100
	v_lshlrev_b64 v[100:101], 2, v[100:101]
	v_lshl_add_u64 v[140:141], s[80:81], 0, v[100:101]
	v_lshl_add_u64 v[136:137], s[98:99], 0, v[100:101]
	v_add_u32_e32 v100, 0xfffffd00, v2
	v_ashrrev_i32_e32 v101, 31, v100
	v_lshlrev_b64 v[100:101], 2, v[100:101]
	v_lshl_add_u64 v[144:145], s[80:81], 0, v[100:101]
	v_lshl_add_u64 v[146:147], s[98:99], 0, v[100:101]
	v_add_u32_e32 v100, 0xfffffe80, v2
	v_ashrrev_i32_e32 v101, 31, v100
	v_lshlrev_b64 v[100:101], 2, v[100:101]
	v_ashrrev_i32_e32 v3, 31, v2
	v_lshl_add_u64 v[102:103], s[30:31], 0, v[34:35]
	v_lshl_add_u64 v[106:107], s[30:31], 0, v[30:31]
	v_lshl_add_u64 v[104:105], s[30:31], 0, v[26:27]
	v_lshl_add_u64 v[120:121], s[30:31], 0, v[22:23]
	v_lshl_add_u64 v[138:139], s[30:31], 0, v[18:19]
	v_lshl_add_u64 v[142:143], s[30:31], 0, v[14:15]
	v_lshl_add_u64 v[150:151], s[80:81], 0, v[100:101]
	v_lshl_add_u64 v[152:153], s[98:99], 0, v[100:101]
	v_lshlrev_b64 v[100:101], 2, v[2:3]
	v_lshl_add_u64 v[148:149], s[30:31], 0, v[10:11]
	v_lshl_add_u64 v[154:155], s[30:31], 0, v[6:7]
	v_lshl_add_u64 v[156:157], s[80:81], 0, v[100:101]
	v_lshl_add_u64 v[158:159], s[98:99], 0, v[100:101]
	global_load_dwordx2 v[100:101], v[120:121], off
	s_nop 0
	global_load_dwordx2 v[104:105], v[104:105], off
	s_nop 0
	global_load_dwordx2 v[124:125], v[106:107], off
	global_load_dwordx2 v[128:129], v[102:103], off
	s_nop 0
	global_load_dwordx2 v[102:103], v[122:123], off
	global_load_dwordx2 v[106:107], v[116:117], off
	global_load_dwordx2 v[126:127], v[112:113], off
	global_load_dwordx2 v[132:133], v[108:109], off
	s_nop 0
	global_load_dwordx2 v[108:109], v[130:131], off
	s_nop 0
	global_load_dwordx2 v[130:131], v[118:119], off
	global_load_dwordx2 v[134:135], v[114:115], off
	global_load_dwordx2 v[160:161], v[110:111], off
	s_nop 0
	global_load_dwordx2 v[110:111], v[154:155], off
	global_load_dwordx2 v[112:113], v[148:149], off
	global_load_dwordx2 v[116:117], v[142:143], off
	global_load_dwordx2 v[120:121], v[138:139], off
	global_load_dwordx2 v[114:115], v[150:151], off
	global_load_dwordx2 v[118:119], v[144:145], off
	global_load_dwordx2 v[122:123], v[140:141], off
	s_nop 0
	global_load_dwordx2 v[138:139], v[156:157], off
	global_load_dwordx2 v[140:141], v[152:153], off
	global_load_dwordx2 v[142:143], v[146:147], off
	s_nop 0
	global_load_dwordx2 v[136:137], v[136:137], off
	s_nop 0
	global_load_dwordx2 v[144:145], v[158:159], off
	v_add_u32_e32 v2, 0xc00, v2
	v_lshl_add_u64 v[6:7], v[6:7], 0, s[92:93]
	v_lshl_add_u64 v[10:11], v[10:11], 0, s[92:93]
	v_lshl_add_u64 v[14:15], v[14:15], 0, s[92:93]
	v_lshl_add_u64 v[18:19], v[18:19], 0, s[92:93]
	v_lshl_add_u64 v[22:23], v[22:23], 0, s[92:93]
	v_lshl_add_u64 v[26:27], v[26:27], 0, s[92:93]
	v_lshl_add_u64 v[30:31], v[30:31], 0, s[92:93]
	v_lshl_add_u64 v[34:35], v[34:35], 0, s[92:93]
	v_lshl_add_u64 v[86:87], s[30:31], 0, v[24:25]
	v_lshl_add_u64 v[24:25], v[24:25], 0, s[90:91]
	s_waitcnt vmcnt(44)
	s_waitcnt vmcnt(40)
	s_waitcnt vmcnt(36)
	s_nop 0
	v_pk_mul_f32 v[84:85], v[36:37], v[98:99]
	v_pk_fma_f32 v[36:37], v[36:37], v[70:71], v[66:67]
	s_waitcnt vmcnt(32)
	s_waitcnt vmcnt(28)
	s_waitcnt vmcnt(24)
	v_cvt_pk_bf16_f32 v0, v84, v85
	v_lshl_add_u64 v[84:85], s[30:31], 0, v[32:33]
	v_pk_mul_f32 v[66:67], v[72:73], v[36:37]
	v_pk_fma_f32 v[36:37], v[64:65], v[36:37], v[62:63]
	global_store_dword v[84:85], v0, off
	v_lshl_add_u64 v[84:85], s[30:31], 0, v[28:29]
	v_cvt_pk_bf16_f32 v0, v66, v67
	v_pk_mul_f32 v[62:63], v[68:69], v[36:37]
	v_pk_fma_f32 v[36:37], v[44:45], v[36:37], v[42:43]
	global_store_dword v[84:85], v0, off
	v_cvt_pk_bf16_f32 v0, v62, v63
	v_pk_mul_f32 v[42:43], v[46:47], v[36:37]
	v_pk_fma_f32 v[36:37], v[40:41], v[36:37], v[38:39]
	global_store_dword v[86:87], v0, off
	v_lshl_add_u64 v[62:63], s[30:31], 0, v[20:21]
	v_cvt_pk_bf16_f32 v0, v42, v43
	v_pk_mul_f32 v[38:39], v[74:75], v[36:37]
	v_pk_fma_f32 v[36:37], v[60:61], v[36:37], v[58:59]
	v_lshl_add_u64 v[64:65], s[30:31], 0, v[16:17]
	global_store_dword v[62:63], v0, off
	v_cvt_pk_bf16_f32 v0, v38, v39
	v_pk_mul_f32 v[38:39], v[80:81], v[36:37]
	v_pk_fma_f32 v[36:37], v[56:57], v[36:37], v[54:55]
	v_lshl_add_u64 v[66:67], s[30:31], 0, v[12:13]
	global_store_dword v[64:65], v0, off
	v_cvt_pk_bf16_f32 v0, v38, v39
	v_pk_mul_f32 v[38:39], v[78:79], v[36:37]
	v_pk_fma_f32 v[36:37], v[52:53], v[36:37], v[50:51]
	v_lshl_add_u64 v[68:69], s[30:31], 0, v[8:9]
	v_lshl_add_u64 v[70:71], s[30:31], 0, v[4:5]
	global_store_dword v[66:67], v0, off
	v_cvt_pk_bf16_f32 v0, v38, v39
	v_pk_mul_f32 v[38:39], v[82:83], v[36:37]
	v_pk_fma_f32 v[36:37], v[76:77], v[36:37], v[48:49]
	v_lshl_add_u64 v[4:5], v[4:5], 0, s[90:91]
	v_lshl_add_u64 v[8:9], v[8:9], 0, s[90:91]
	v_lshl_add_u64 v[12:13], v[12:13], 0, s[90:91]
	v_lshl_add_u64 v[16:17], v[16:17], 0, s[90:91]
	v_lshl_add_u64 v[20:21], v[20:21], 0, s[90:91]
	v_lshl_add_u64 v[28:29], v[28:29], 0, s[90:91]
	v_lshl_add_u64 v[32:33], v[32:33], 0, s[90:91]
	global_store_dword v[68:69], v0, off
	v_cvt_pk_bf16_f32 v0, v38, v39
	global_store_dword v[70:71], v0, off
	s_add_i32 s10, s10, 1
	s_cmp_eq_u32 s10, 8
	s_cbranch_scc1 .Lscan_last
	v_add_u32_e32 v38, 0xfffff580, v2
	v_ashrrev_i32_e32 v39, 31, v38
	v_lshlrev_b64 v[38:39], 2, v[38:39]
	v_lshl_add_u64 v[46:47], s[80:81], 0, v[38:39]
	v_lshl_add_u64 v[48:49], s[98:99], 0, v[38:39]
	v_add_u32_e32 v38, 0xfffff700, v2
	v_ashrrev_i32_e32 v39, 31, v38
	v_lshlrev_b64 v[38:39], 2, v[38:39]
	v_lshl_add_u64 v[50:51], s[80:81], 0, v[38:39]
	v_lshl_add_u64 v[52:53], s[98:99], 0, v[38:39]
	v_add_u32_e32 v38, 0xfffff880, v2
	v_ashrrev_i32_e32 v39, 31, v38
	v_lshlrev_b64 v[38:39], 2, v[38:39]
	v_lshl_add_u64 v[54:55], s[80:81], 0, v[38:39]
	v_lshl_add_u64 v[56:57], s[98:99], 0, v[38:39]
	v_add_u32_e32 v38, 0xfffffa00, v2
	v_ashrrev_i32_e32 v39, 31, v38
	v_lshlrev_b64 v[38:39], 2, v[38:39]
	v_lshl_add_u64 v[60:61], s[80:81], 0, v[38:39]
	v_lshl_add_u64 v[68:69], s[98:99], 0, v[38:39]
	v_add_u32_e32 v38, 0xfffffb80, v2
	v_ashrrev_i32_e32 v39, 31, v38
	v_lshlrev_b64 v[38:39], 2, v[38:39]
	v_lshl_add_u64 v[78:79], s[80:81], 0, v[38:39]
	v_lshl_add_u64 v[74:75], s[98:99], 0, v[38:39]
	v_add_u32_e32 v38, 0xfffffd00, v2
	v_ashrrev_i32_e32 v39, 31, v38
	v_lshlrev_b64 v[38:39], 2, v[38:39]
	v_lshl_add_u64 v[82:83], s[80:81], 0, v[38:39]
	v_lshl_add_u64 v[84:85], s[98:99], 0, v[38:39]
	v_add_u32_e32 v38, 0xfffffe80, v2
	v_ashrrev_i32_e32 v39, 31, v38
	v_lshlrev_b64 v[38:39], 2, v[38:39]
	v_ashrrev_i32_e32 v3, 31, v2
	v_lshl_add_u64 v[40:41], s[30:31], 0, v[34:35]
	v_lshl_add_u64 v[44:45], s[30:31], 0, v[30:31]
	v_lshl_add_u64 v[42:43], s[30:31], 0, v[26:27]
	v_lshl_add_u64 v[58:59], s[30:31], 0, v[22:23]
	v_lshl_add_u64 v[76:77], s[30:31], 0, v[18:19]
	v_lshl_add_u64 v[80:81], s[30:31], 0, v[14:15]
	v_lshl_add_u64 v[88:89], s[80:81], 0, v[38:39]
	v_lshl_add_u64 v[90:91], s[98:99], 0, v[38:39]
	v_lshlrev_b64 v[38:39], 2, v[2:3]
	v_lshl_add_u64 v[86:87], s[30:31], 0, v[10:11]
	v_lshl_add_u64 v[92:93], s[30:31], 0, v[6:7]
	v_lshl_add_u64 v[94:95], s[80:81], 0, v[38:39]
	v_lshl_add_u64 v[96:97], s[98:99], 0, v[38:39]
	global_load_dwordx2 v[38:39], v[58:59], off
	s_nop 0
	global_load_dwordx2 v[42:43], v[42:43], off
	s_nop 0
	global_load_dwordx2 v[62:63], v[44:45], off
	global_load_dwordx2 v[66:67], v[40:41], off
	s_nop 0
	global_load_dwordx2 v[40:41], v[60:61], off
	global_load_dwordx2 v[44:45], v[54:55], off
	global_load_dwordx2 v[64:65], v[50:51], off
	global_load_dwordx2 v[70:71], v[46:47], off
	s_nop 0
	global_load_dwordx2 v[46:47], v[68:69], off
	s_nop 0
	global_load_dwordx2 v[68:69], v[56:57], off
	global_load_dwordx2 v[72:73], v[52:53], off
	global_load_dwordx2 v[98:99], v[48:49], off
	s_nop 0
	global_load_dwordx2 v[48:49], v[92:93], off
	global_load_dwordx2 v[50:51], v[86:87], off
	global_load_dwordx2 v[54:55], v[80:81], off
	global_load_dwordx2 v[58:59], v[76:77], off
	global_load_dwordx2 v[52:53], v[88:89], off
	global_load_dwordx2 v[56:57], v[82:83], off
	global_load_dwordx2 v[60:61], v[78:79], off
	s_nop 0
	global_load_dwordx2 v[76:77], v[94:95], off
	global_load_dwordx2 v[78:79], v[90:91], off
	global_load_dwordx2 v[80:81], v[84:85], off
	s_nop 0
	global_load_dwordx2 v[74:75], v[74:75], off
	s_nop 0
	global_load_dwordx2 v[82:83], v[96:97], off
	v_add_u32_e32 v2, 0xc00, v2
	v_lshl_add_u64 v[6:7], v[6:7], 0, s[92:93]
	v_lshl_add_u64 v[10:11], v[10:11], 0, s[92:93]
	v_lshl_add_u64 v[14:15], v[14:15], 0, s[92:93]
	v_lshl_add_u64 v[18:19], v[18:19], 0, s[92:93]
	v_lshl_add_u64 v[22:23], v[22:23], 0, s[92:93]
	v_lshl_add_u64 v[26:27], v[26:27], 0, s[92:93]
	v_lshl_add_u64 v[30:31], v[30:31], 0, s[92:93]
	v_lshl_add_u64 v[34:35], v[34:35], 0, s[92:93]
	v_lshl_add_u64 v[148:149], s[30:31], 0, v[24:25]
	v_lshl_add_u64 v[24:25], v[24:25], 0, s[90:91]
	s_waitcnt vmcnt(44)
	s_waitcnt vmcnt(40)
	s_waitcnt vmcnt(36)
	s_nop 0
	v_pk_mul_f32 v[146:147], v[36:37], v[160:161]
	v_pk_fma_f32 v[36:37], v[36:37], v[132:133], v[128:129]
	s_waitcnt vmcnt(32)
	s_waitcnt vmcnt(28)
	s_waitcnt vmcnt(24)
	v_cvt_pk_bf16_f32 v0, v146, v147
	v_lshl_add_u64 v[146:147], s[30:31], 0, v[32:33]
	v_pk_mul_f32 v[128:129], v[134:135], v[36:37]
	v_pk_fma_f32 v[36:37], v[126:127], v[36:37], v[124:125]
	global_store_dword v[146:147], v0, off
	v_lshl_add_u64 v[146:147], s[30:31], 0, v[28:29]
	v_cvt_pk_bf16_f32 v0, v128, v129
	v_pk_mul_f32 v[124:125], v[130:131], v[36:37]
	v_pk_fma_f32 v[36:37], v[106:107], v[36:37], v[104:105]
	global_store_dword v[146:147], v0, off
	v_cvt_pk_bf16_f32 v0, v124, v125
	v_pk_mul_f32 v[104:105], v[108:109], v[36:37]
	v_pk_fma_f32 v[36:37], v[102:103], v[36:37], v[100:101]
	global_store_dword v[148:149], v0, off
	v_lshl_add_u64 v[124:125], s[30:31], 0, v[20:21]
	v_cvt_pk_bf16_f32 v0, v104, v105
	v_pk_mul_f32 v[100:101], v[136:137], v[36:37]
	v_pk_fma_f32 v[36:37], v[122:123], v[36:37], v[120:121]
	v_lshl_add_u64 v[126:127], s[30:31], 0, v[16:17]
	global_store_dword v[124:125], v0, off
	v_cvt_pk_bf16_f32 v0, v100, v101
	v_pk_mul_f32 v[100:101], v[142:143], v[36:37]
	v_pk_fma_f32 v[36:37], v[118:119], v[36:37], v[116:117]
	v_lshl_add_u64 v[128:129], s[30:31], 0, v[12:13]
	global_store_dword v[126:127], v0, off
	v_cvt_pk_bf16_f32 v0, v100, v101
	v_pk_mul_f32 v[100:101], v[140:141], v[36:37]
	v_pk_fma_f32 v[36:37], v[114:115], v[36:37], v[112:113]
	v_lshl_add_u64 v[130:131], s[30:31], 0, v[8:9]
	v_lshl_add_u64 v[132:133], s[30:31], 0, v[4:5]
	global_store_dword v[128:129], v0, off
	v_cvt_pk_bf16_f32 v0, v100, v101
	v_pk_mul_f32 v[100:101], v[144:145], v[36:37]
	v_pk_fma_f32 v[36:37], v[138:139], v[36:37], v[110:111]
	v_lshl_add_u64 v[4:5], v[4:5], 0, s[90:91]
	v_lshl_add_u64 v[8:9], v[8:9], 0, s[90:91]
	v_lshl_add_u64 v[12:13], v[12:13], 0, s[90:91]
	v_lshl_add_u64 v[16:17], v[16:17], 0, s[90:91]
	v_lshl_add_u64 v[20:21], v[20:21], 0, s[90:91]
	v_lshl_add_u64 v[28:29], v[28:29], 0, s[90:91]
	v_lshl_add_u64 v[32:33], v[32:33], 0, s[90:91]
	global_store_dword v[130:131], v0, off
	v_cvt_pk_bf16_f32 v0, v100, v101
	global_store_dword v[132:133], v0, off
	s_branch .Lscan_loop
.Lscan_last:
	v_lshl_add_u64 v[148:149], s[30:31], 0, v[24:25]
	v_lshl_add_u64 v[24:25], v[24:25], 0, s[90:91]
	s_waitcnt vmcnt(20)
	s_waitcnt vmcnt(16)
	s_waitcnt vmcnt(12)
	s_nop 0
	v_pk_mul_f32 v[146:147], v[36:37], v[160:161]
	v_pk_fma_f32 v[36:37], v[36:37], v[132:133], v[128:129]
	s_waitcnt vmcnt(8)
	s_waitcnt vmcnt(4)
	s_waitcnt vmcnt(0)
	v_cvt_pk_bf16_f32 v0, v146, v147
	v_lshl_add_u64 v[146:147], s[30:31], 0, v[32:33]
	v_pk_mul_f32 v[128:129], v[134:135], v[36:37]
	v_pk_fma_f32 v[36:37], v[126:127], v[36:37], v[124:125]
	global_store_dword v[146:147], v0, off
	v_lshl_add_u64 v[146:147], s[30:31], 0, v[28:29]
	v_cvt_pk_bf16_f32 v0, v128, v129
	v_pk_mul_f32 v[124:125], v[130:131], v[36:37]
	v_pk_fma_f32 v[36:37], v[106:107], v[36:37], v[104:105]
	global_store_dword v[146:147], v0, off
	v_cvt_pk_bf16_f32 v0, v124, v125
	v_pk_mul_f32 v[104:105], v[108:109], v[36:37]
	v_pk_fma_f32 v[36:37], v[102:103], v[36:37], v[100:101]
	global_store_dword v[148:149], v0, off
	v_lshl_add_u64 v[124:125], s[30:31], 0, v[20:21]
	v_cvt_pk_bf16_f32 v0, v104, v105
	v_pk_mul_f32 v[100:101], v[136:137], v[36:37]
	v_pk_fma_f32 v[36:37], v[122:123], v[36:37], v[120:121]
	v_lshl_add_u64 v[126:127], s[30:31], 0, v[16:17]
	global_store_dword v[124:125], v0, off
	v_cvt_pk_bf16_f32 v0, v100, v101
	v_pk_mul_f32 v[100:101], v[142:143], v[36:37]
	v_pk_fma_f32 v[36:37], v[118:119], v[36:37], v[116:117]
	v_lshl_add_u64 v[128:129], s[30:31], 0, v[12:13]
	global_store_dword v[126:127], v0, off
	v_cvt_pk_bf16_f32 v0, v100, v101
	v_pk_mul_f32 v[100:101], v[140:141], v[36:37]
	v_pk_fma_f32 v[36:37], v[114:115], v[36:37], v[112:113]
	v_lshl_add_u64 v[130:131], s[30:31], 0, v[8:9]
	v_lshl_add_u64 v[132:133], s[30:31], 0, v[4:5]
	global_store_dword v[128:129], v0, off
	v_cvt_pk_bf16_f32 v0, v100, v101
	v_pk_mul_f32 v[100:101], v[144:145], v[36:37]
	v_pk_fma_f32 v[36:37], v[138:139], v[36:37], v[110:111]
	v_lshl_add_u64 v[4:5], v[4:5], 0, s[90:91]
	v_lshl_add_u64 v[8:9], v[8:9], 0, s[90:91]
	v_lshl_add_u64 v[12:13], v[12:13], 0, s[90:91]
	v_lshl_add_u64 v[16:17], v[16:17], 0, s[90:91]
	v_lshl_add_u64 v[20:21], v[20:21], 0, s[90:91]
	v_lshl_add_u64 v[28:29], v[28:29], 0, s[90:91]
	v_lshl_add_u64 v[32:33], v[32:33], 0, s[90:91]
	global_store_dword v[130:131], v0, off
	v_cvt_pk_bf16_f32 v0, v100, v101
	global_store_dword v[132:133], v0, off
	s_branch .LBB0_323
